# v12: mixer workgroups pace their channel-group loop (s_sleep 25) so the GLA scan workgroups see less HBM contention in phase 3
# speedup vs baseline: 1.0017x; 1.0017x over previous
; #define LAS __attribute__((address_space(3)))
; __device__ __forceinline__ float bflo(unsigned w) { return __uint_as_float(w << 16); }
; __device__ __forceinline__ float bfhi(unsigned w) { return __uint_as_float(w & 0xffff0000u); }
; __device__ __forceinline__ unsigned pk2(float lo, float hi) { return f2bf(lo) | (f2bf(hi) << 16); }
; __device__ __forceinline__ void phase_mixer_a(const Params& P, LAS unsigned char* lds, int ustart, int ustride, bool dry) {
;     ...
;             for (int i = 0; i < 4; ++i) {
;                 const int item = tid + 512 * i, c8 = item & 15, s = item >> 4;
;                 const u32x4 gv = pgv[i];
;                 const float mean = stats[2 * s], rstd = stats[2 * s + 1];
;                 const f32x4 g0 = *(const f32x4*)(P.ln_v_g + h * 128 + c8 * 8), g1 = *(const f32x4*)(P.ln_v_g + h * 128 + c8 * 8 + 4);
;                 const f32x4 b0 = *(const f32x4*)(P.ln_v_b + h * 128 + c8 * 8), b1 = *(const f32x4*)(P.ln_v_b + h * 128 + c8 * 8 + 4);
;                 u32x4 o;
;                 o.x = pk2((bflo(gv.x) - mean) * rstd * g0[0] + b0[0], (bfhi(gv.x) - mean) * rstd * g0[1] + b0[1]);
;                 o.y = pk2((bflo(gv.y) - mean) * rstd * g0[2] + b0[2], (bfhi(gv.y) - mean) * rstd * g0[3] + b0[3]);
;                 o.z = pk2((bflo(gv.z) - mean) * rstd * g1[0] + b1[0], (bfhi(gv.z) - mean) * rstd * g1[1] + b1[1]);
;                 o.w = pk2((bflo(gv.w) - mean) * rstd * g1[2] + b1[2], (bfhi(gv.w) - mean) * rstd * g1[3] + b1[3]);
;                 *(LAS u32x4*)(lds + s * VN_P + c8 * 16) = o;
;                 *(LAS u32x4*)(lds + W_OFF + s * W_P + c8 * 16) = *(const u32x4*)(WsT + h * 16384 + item * 8);
;             }
;             __syncthreads();
.LBB0_632:
	s_sleep 25
	v_lshl_add_u64 v[16:17], v[62:63], 0, s[6:7]
	global_load_dwordx4 v[24:27], v[16:17], off offset:-16
	v_lshl_add_u64 v[20:21], v[66:67], 0, s[6:7]
	global_load_dwordx4 v[28:31], v[20:21], off offset:-16
	s_nop 0
	global_load_dwordx4 v[16:19], v[16:17], off
	s_nop 0
	global_load_dwordx4 v[20:23], v[20:21], off
	s_nop 0
	global_load_dwordx4 v[168:171], v[126:127], off
	global_load_dwordx4 v[172:175], v[124:125], off
	ds_read_b64 v[128:129], v151
	s_waitcnt vmcnt(9)
	v_lshlrev_b32_e32 v131, 16, v1
	v_lshlrev_b32_e32 v130, 16, v0
	v_and_b32_e32 v177, 0xffff0000, v1
	v_and_b32_e32 v176, 0xffff0000, v0
	v_lshlrev_b32_e32 v179, 16, v3
	v_lshlrev_b32_e32 v178, 16, v2
	v_and_b32_e32 v181, 0xffff0000, v3
	v_and_b32_e32 v180, 0xffff0000, v2
	s_waitcnt lgkmcnt(0)
	v_pk_add_f32 v[130:131], v[130:131], v[128:129] op_sel_hi:[1,0] neg_lo:[0,1] neg_hi:[0,1]
	v_pk_add_f32 v[176:177], v[176:177], v[128:129] op_sel_hi:[1,0] neg_lo:[0,1] neg_hi:[0,1]
	v_pk_add_f32 v[178:179], v[178:179], v[128:129] op_sel_hi:[1,0] neg_lo:[0,1] neg_hi:[0,1]
	v_pk_add_f32 v[180:181], v[180:181], v[128:129] op_sel_hi:[1,0] neg_lo:[0,1] neg_hi:[0,1]
	v_pk_mul_f32 v[188:189], v[128:129], v[130:131] op_sel:[1,0]
	v_pk_mul_f32 v[176:177], v[128:129], v[176:177] op_sel:[1,0]
	v_pk_mul_f32 v[178:179], v[128:129], v[178:179] op_sel:[1,0]
	v_pk_mul_f32 v[180:181], v[128:129], v[180:181] op_sel:[1,0]
	s_waitcnt vmcnt(8)
	v_lshlrev_b32_e32 v183, 16, v5
	v_lshlrev_b32_e32 v182, 16, v4
	v_and_b32_e32 v185, 0xffff0000, v5
	v_and_b32_e32 v184, 0xffff0000, v4
	v_lshlrev_b32_e32 v187, 16, v7
	v_lshlrev_b32_e32 v186, 16, v6
	s_cmpk_lg_i32 s16, 0x700
	s_waitcnt vmcnt(4)
	v_mov_b32_e32 v130, v28
	v_mov_b32_e32 v128, v24
	v_mov_b32_e32 v129, v26
	v_mov_b32_e32 v131, v30
	v_mov_b32_e32 v26, v25
	v_mov_b32_e32 v30, v29
	s_waitcnt vmcnt(3)
	v_mov_b32_e32 v24, v16
	v_mov_b32_e32 v25, v18
	s_waitcnt vmcnt(2)
	v_mov_b32_e32 v28, v20
	v_mov_b32_e32 v29, v22
	v_mov_b32_e32 v18, v17
	v_mov_b32_e32 v22, v21
	v_pk_fma_f32 v[16:17], v[188:189], v[128:129], v[130:131]
	v_pk_fma_f32 v[20:21], v[176:177], v[26:27], v[30:31]
	v_pk_fma_f32 v[176:177], v[178:179], v[24:25], v[28:29]
	v_pk_fma_f32 v[178:179], v[180:181], v[18:19], v[22:23]
	v_cvt_pk_bf16_f32 v255, v16, v20
	v_cvt_pk_bf16_f32 v254, v17, v21
	v_cvt_pk_bf16_f32 v179, v177, v179
	v_cvt_pk_bf16_f32 v178, v176, v178
	v_mov_b32_e32 v177, v254
	v_mov_b32_e32 v176, v255
	ds_write_b128 v152, v[176:179]
	s_waitcnt vmcnt(1)
	ds_write_b128 v153, v[168:171] offset:36864
	ds_read_b64 v[16:17], v154
	global_load_dwordx4 v[168:171], v[122:123], off
	v_and_b32_e32 v21, 0xffff0000, v7
	v_and_b32_e32 v20, 0xffff0000, v6
	s_waitcnt lgkmcnt(0)
	v_pk_add_f32 v[176:177], v[182:183], v[16:17] op_sel_hi:[1,0] neg_lo:[0,1] neg_hi:[0,1]
	v_pk_add_f32 v[178:179], v[184:185], v[16:17] op_sel_hi:[1,0] neg_lo:[0,1] neg_hi:[0,1]
	v_pk_add_f32 v[180:181], v[186:187], v[16:17] op_sel_hi:[1,0] neg_lo:[0,1] neg_hi:[0,1]
	v_pk_add_f32 v[20:21], v[20:21], v[16:17] op_sel_hi:[1,0] neg_lo:[0,1] neg_hi:[0,1]
	v_pk_mul_f32 v[176:177], v[16:17], v[176:177] op_sel:[1,0]
	v_pk_mul_f32 v[178:179], v[16:17], v[178:179] op_sel:[1,0]
	v_pk_mul_f32 v[180:181], v[16:17], v[180:181] op_sel:[1,0]
	v_pk_mul_f32 v[16:17], v[16:17], v[20:21] op_sel:[1,0]
	v_pk_fma_f32 v[20:21], v[128:129], v[176:177], v[130:131]
	v_pk_fma_f32 v[16:17], v[18:19], v[16:17], v[22:23]
	v_pk_fma_f32 v[176:177], v[26:27], v[178:179], v[30:31]
	v_pk_fma_f32 v[178:179], v[24:25], v[180:181], v[28:29]
	s_nop 0
	v_cvt_pk_bf16_f32 v233, v178, v16
	v_cvt_pk_bf16_f32 v232, v179, v17
	v_cvt_pk_bf16_f32 v234, v21, v177
	v_cvt_pk_bf16_f32 v235, v20, v176
	v_mov_b32_e32 v179, v232
	v_mov_b32_e32 v178, v233
	v_mov_b32_e32 v177, v234
	v_mov_b32_e32 v176, v235
	ds_write_b128 v155, v[176:179]
	s_waitcnt vmcnt(1)
	ds_write_b128 v156, v[172:175] offset:36864
	ds_read_b64 v[16:17], v157
	v_and_b32_e32 v173, 0xffff0000, v9
	v_and_b32_e32 v172, 0xffff0000, v8
	v_lshlrev_b32_e32 v21, 16, v9
	v_lshlrev_b32_e32 v20, 16, v8
	s_waitcnt lgkmcnt(0)
	v_pk_add_f32 v[172:173], v[172:173], v[16:17] op_sel_hi:[1,0] neg_lo:[0,1] neg_hi:[0,1]
	v_and_b32_e32 v181, 0xffff0000, v11
	v_pk_mul_f32 v[172:173], v[16:17], v[172:173] op_sel:[1,0]
	v_and_b32_e32 v180, 0xffff0000, v10
	v_pk_fma_f32 v[176:177], v[26:27], v[172:173], v[30:31]
	v_lshlrev_b32_e32 v173, 16, v11
	v_lshlrev_b32_e32 v172, 16, v10
	v_pk_add_f32 v[172:173], v[172:173], v[16:17] op_sel_hi:[1,0] neg_lo:[0,1] neg_hi:[0,1]
	v_pk_add_f32 v[20:21], v[20:21], v[16:17] op_sel_hi:[1,0] neg_lo:[0,1] neg_hi:[0,1]
	v_pk_mul_f32 v[172:173], v[16:17], v[172:173] op_sel:[1,0]
	v_pk_add_f32 v[180:181], v[180:181], v[16:17] op_sel_hi:[1,0] neg_lo:[0,1] neg_hi:[0,1]
	v_pk_fma_f32 v[178:179], v[24:25], v[172:173], v[28:29]
	global_load_dwordx4 v[172:175], v[120:121], off
	v_pk_mul_f32 v[20:21], v[16:17], v[20:21] op_sel:[1,0]
	v_pk_mul_f32 v[16:17], v[16:17], v[180:181] op_sel:[1,0]
	v_pk_fma_f32 v[20:21], v[128:129], v[20:21], v[130:131]
	v_pk_fma_f32 v[16:17], v[18:19], v[16:17], v[22:23]
	s_nop 0
	v_cvt_pk_bf16_f32 v252, v178, v16
	v_cvt_pk_bf16_f32 v237, v179, v17
	v_cvt_pk_bf16_f32 v253, v21, v177
	v_cvt_pk_bf16_f32 v254, v20, v176
	v_mov_b32_e32 v179, v237
	v_mov_b32_e32 v178, v252
	v_mov_b32_e32 v177, v253
	v_mov_b32_e32 v176, v254
	ds_write_b128 v158, v[176:179]
	s_waitcnt vmcnt(1)
	ds_write_b128 v159, v[168:171] offset:36864
	ds_read_b64 v[16:17], v160
	v_lshlrev_b32_e32 v21, 16, v13
	v_lshlrev_b32_e32 v20, 16, v12
	s_waitcnt lgkmcnt(0)
	v_pk_add_f32 v[20:21], v[20:21], v[16:17] op_sel_hi:[1,0] neg_lo:[0,1] neg_hi:[0,1]
	s_nop 0
	v_pk_mul_f32 v[20:21], v[16:17], v[20:21] op_sel:[1,0]
	s_nop 0
	v_pk_fma_f32 v[20:21], v[128:129], v[20:21], v[130:131]
	v_and_b32_e32 v129, 0xffff0000, v13
	v_and_b32_e32 v128, 0xffff0000, v12
	v_pk_add_f32 v[128:129], v[128:129], v[16:17] op_sel_hi:[1,0] neg_lo:[0,1] neg_hi:[0,1]
	s_nop 0
	v_pk_mul_f32 v[128:129], v[16:17], v[128:129] op_sel:[1,0]
	s_nop 0
	v_pk_fma_f32 v[26:27], v[26:27], v[128:129], v[30:31]
	v_lshlrev_b32_e32 v31, 16, v15
	v_lshlrev_b32_e32 v30, 16, v14
	v_pk_add_f32 v[30:31], v[30:31], v[16:17] op_sel_hi:[1,0] neg_lo:[0,1] neg_hi:[0,1]
	s_nop 0
	v_pk_mul_f32 v[30:31], v[16:17], v[30:31] op_sel:[1,0]
	s_nop 0
	v_pk_fma_f32 v[24:25], v[24:25], v[30:31], v[28:29]
	v_and_b32_e32 v29, 0xffff0000, v15
	v_and_b32_e32 v28, 0xffff0000, v14
	v_pk_add_f32 v[28:29], v[28:29], v[16:17] op_sel_hi:[1,0] neg_lo:[0,1] neg_hi:[0,1]
	s_nop 0
	v_pk_mul_f32 v[16:17], v[16:17], v[28:29] op_sel:[1,0]
	s_nop 0
	v_pk_fma_f32 v[16:17], v[18:19], v[16:17], v[22:23]
	s_nop 0
	v_cvt_pk_bf16_f32 v232, v24, v16
	v_cvt_pk_bf16_f32 v255, v25, v17
	v_cvt_pk_bf16_f32 v234, v20, v26
	v_cvt_pk_bf16_f32 v233, v21, v27
	v_mov_b32_e32 v19, v255
	v_mov_b32_e32 v18, v232
	v_mov_b32_e32 v17, v233
	v_mov_b32_e32 v16, v234
	ds_write_b128 v161, v[16:19]
	s_waitcnt vmcnt(0)
	ds_write_b128 v162, v[172:175] offset:36864
	s_waitcnt lgkmcnt(0)
	s_barrier
; __device__ __forceinline__ void phase_mixer_a(const Params& P, LAS unsigned char* lds, int ustart, int ustride, bool dry) {
;     ...
;             if (h + 1 < 8) {
; #pragma unroll
;                 for (int i = 0; i < 4; ++i) { const int item = tid + 512 * i, c8 = item & 15, s = item >> 4;
;                     pgv[i] = *(const u32x4*)(PJ + T_GV + (size_t)(r0 + s) * 1024 + (h + 1) * 128 + c8 * 8); }
;             }
	s_cbranch_scc0 .LBB0_631
	v_lshl_add_u64 v[12:13], v[86:87], 0, s[16:17]
	v_lshl_add_u64 v[8:9], v[84:85], 0, s[16:17]
	v_lshl_add_u64 v[4:5], v[82:83], 0, s[16:17]
	v_lshl_add_u64 v[0:1], v[80:81], 0, s[16:17]
	global_load_dwordx4 v[0:3], v[0:1], off
	s_nop 0
	global_load_dwordx4 v[4:7], v[4:5], off
	s_nop 0
	global_load_dwordx4 v[8:11], v[8:9], off
	s_nop 0
	global_load_dwordx4 v[12:15], v[12:13], off
	s_branch .LBB0_631
